# seams: the (n-2)-th arriving WG of each XCD starts an early L2 write-back while it waits
# baseline (speedup 1.0000x reference)
.LBB0_147:
	s_or_b64 exec, exec, s[16:17]
	v_cvt_f32_u32_e32 v4, v2
	s_waitcnt vmcnt(0)
	v_readfirstlane_b32 s3, v3
	v_sub_u32_e32 v3, 0, v2
	v_rcp_iflag_f32_e32 v4, v4
	v_add_u32_e32 v5, s3, v1
	v_mul_f32_e32 v4, 0x4f7ffffe, v4
	v_cvt_u32_f32_e32 v4, v4
	v_mul_lo_u32 v1, v3, v4
	v_mul_hi_u32 v1, v4, v1
	v_add_u32_e32 v1, v4, v1
	v_mul_hi_u32 v1, v5, v1
	v_mul_lo_u32 v3, v1, v2
	v_sub_u32_e32 v3, v5, v3
	v_add_u32_e32 v4, 1, v1
	v_cmp_ge_u32_e32 vcc, v3, v2
	s_nop 1
	v_cndmask_b32_e32 v1, v1, v4, vcc
	v_sub_u32_e32 v4, v3, v2
	v_cndmask_b32_e32 v3, v3, v4, vcc
	v_add_u32_e32 v4, 1, v1
	v_cmp_ge_u32_e32 vcc, v3, v2
	v_add_u32_e32 v3, 1, v5
	s_nop 0
	v_cndmask_b32_e32 v1, v1, v4, vcc
	v_mul_lo_u32 v4, v2, v1
	v_add_u32_e32 v2, v4, v2
	v_cmp_ne_u32_e32 vcc, v3, v2
	s_and_saveexec_b64 s[8:9], vcc
	s_xor_b64 s[8:9], exec, s[8:9]
	s_cbranch_execz .LBB0_161
	v_add_u32_e32 v4, 2, v3
	v_cmp_eq_u32_e32 vcc, v4, v2
	s_cbranch_vccz .Lnoflush_0
	buffer_wbl2 sc1
.Lnoflush_0:
	s_waitcnt lgkmcnt(0)
	v_mov_b32_e32 v0, 0x3100
	global_load_dword v0, v0, s[80:81] offset:1024 sc1
	s_add_u32 s20, s80, 0x3500
	s_addc_u32 s21, s81, 0
	s_waitcnt vmcnt(0)
	v_cmp_eq_u32_e32 vcc, v0, v1
	s_and_saveexec_b64 s[16:17], vcc
	s_cbranch_execz .LBB0_160
	s_add_u32 s18, s88, 0x10200
	s_addc_u32 s19, s89, 0
	s_mov_b32 s3, 1
	s_mov_b64 s[22:23], 0
	v_mov_b32_e32 v0, 0
	s_branch .LBB0_151

.LBB0_279:
	s_or_b64 exec, exec, s[10:11]
	v_cvt_f32_u32_e32 v4, v2
	s_waitcnt vmcnt(0)
	v_readfirstlane_b32 s3, v3
	v_sub_u32_e32 v3, 0, v2
	v_rcp_iflag_f32_e32 v4, v4
	v_add_u32_e32 v5, s3, v1
	v_mul_f32_e32 v4, 0x4f7ffffe, v4
	v_cvt_u32_f32_e32 v4, v4
	v_mul_lo_u32 v1, v3, v4
	v_mul_hi_u32 v1, v4, v1
	v_add_u32_e32 v1, v4, v1
	v_mul_hi_u32 v1, v5, v1
	v_mul_lo_u32 v3, v1, v2
	v_sub_u32_e32 v3, v5, v3
	v_add_u32_e32 v4, 1, v1
	v_cmp_ge_u32_e32 vcc, v3, v2
	s_nop 1
	v_cndmask_b32_e32 v1, v1, v4, vcc
	v_sub_u32_e32 v4, v3, v2
	v_cndmask_b32_e32 v3, v3, v4, vcc
	v_add_u32_e32 v4, 1, v1
	v_cmp_ge_u32_e32 vcc, v3, v2
	v_add_u32_e32 v3, 1, v5
	s_nop 0
	v_cndmask_b32_e32 v1, v1, v4, vcc
	v_mul_lo_u32 v4, v2, v1
	v_add_u32_e32 v2, v4, v2
	v_cmp_ne_u32_e32 vcc, v3, v2
	s_and_saveexec_b64 s[8:9], vcc
	s_xor_b64 s[8:9], exec, s[8:9]
	s_cbranch_execz .LBB0_293
	v_add_u32_e32 v4, 2, v3
	v_cmp_eq_u32_e32 vcc, v4, v2
	s_cbranch_vccz .Lnoflush_1
	buffer_wbl2 sc1
.Lnoflush_1:
	s_waitcnt lgkmcnt(0)
	v_mov_b32_e32 v0, 0x3100
	global_load_dword v0, v0, s[80:81] offset:1024 sc1
	s_add_u32 s16, s80, 0x3500
	s_addc_u32 s17, s81, 0
	s_waitcnt vmcnt(0)
	v_cmp_eq_u32_e32 vcc, v0, v1
	s_and_saveexec_b64 s[10:11], vcc
	s_cbranch_execz .LBB0_292
	s_add_u32 s12, s88, 0x10200
	s_addc_u32 s13, s89, 0
	s_mov_b32 s3, 1
	s_mov_b64 s[18:19], 0
	v_mov_b32_e32 v0, 0
	s_branch .LBB0_283

.Lnoflush_2:
	s_waitcnt lgkmcnt(0)
	v_mov_b32_e32 v0, 0x3100
	global_load_dword v0, v0, s[80:81] offset:1024 sc1
	s_add_u32 s14, s80, 0x3500
	s_addc_u32 s15, s81, 0
	s_waitcnt vmcnt(0)
	v_cmp_eq_u32_e32 vcc, v0, v1
	s_and_saveexec_b64 s[10:11], vcc
	s_cbranch_execz .LBB0_462
	s_add_u32 s12, s88, 0x10200
	s_addc_u32 s13, s89, 0
	s_mov_b32 s3, 1
	s_mov_b64 s[16:17], 0
	v_mov_b32_e32 v0, 0
	s_branch .LBB0_453

.LBB0_627:
	s_or_b64 exec, exec, s[8:9]
	v_cvt_f32_u32_e32 v4, v2
	s_waitcnt vmcnt(0)
	v_readfirstlane_b32 s3, v3
	v_sub_u32_e32 v3, 0, v2
	v_rcp_iflag_f32_e32 v4, v4
	v_add_u32_e32 v5, s3, v1
	v_mul_f32_e32 v4, 0x4f7ffffe, v4
	v_cvt_u32_f32_e32 v4, v4
	v_mul_lo_u32 v1, v3, v4
	v_mul_hi_u32 v1, v4, v1
	v_add_u32_e32 v1, v4, v1
	v_mul_hi_u32 v1, v5, v1
	v_mul_lo_u32 v3, v1, v2
	v_sub_u32_e32 v3, v5, v3
	v_add_u32_e32 v4, 1, v1
	v_cmp_ge_u32_e32 vcc, v3, v2
	s_nop 1
	v_cndmask_b32_e32 v1, v1, v4, vcc
	v_sub_u32_e32 v4, v3, v2
	v_cndmask_b32_e32 v3, v3, v4, vcc
	v_add_u32_e32 v4, 1, v1
	v_cmp_ge_u32_e32 vcc, v3, v2
	v_add_u32_e32 v3, 1, v5
	s_nop 0
	v_cndmask_b32_e32 v1, v1, v4, vcc
	v_mul_lo_u32 v4, v2, v1
	v_add_u32_e32 v2, v4, v2
	v_cmp_ne_u32_e32 vcc, v3, v2
	s_and_saveexec_b64 s[6:7], vcc
	s_xor_b64 s[6:7], exec, s[6:7]
	s_cbranch_execz .LBB0_641
	v_add_u32_e32 v4, 2, v3
	v_cmp_eq_u32_e32 vcc, v4, v2
	s_cbranch_vccz .Lnoflush_4
	buffer_wbl2 sc1
.Lnoflush_4:
	s_waitcnt lgkmcnt(0)
	v_mov_b32_e32 v0, 0x3100
	global_load_dword v0, v0, s[80:81] offset:1024 sc1
	s_add_u32 s12, s80, 0x3500
	s_addc_u32 s13, s81, 0
	s_waitcnt vmcnt(0)
	v_cmp_eq_u32_e32 vcc, v0, v1
	s_and_saveexec_b64 s[8:9], vcc
	s_cbranch_execz .LBB0_640
	s_add_u32 s10, s88, 0x10200
	s_addc_u32 s11, s89, 0
	s_mov_b32 s3, 1
	s_mov_b64 s[16:17], 0
	v_mov_b32_e32 v0, 0
	s_branch .LBB0_631
